# attention loop: rare paths (rescale, tile mask) moved out of line so the common path has no taken branch; mask via scalar test, v_max3 tree
# speedup vs baseline: 1.0087x; 1.0087x over previous
; template <int KB> __device__ __forceinline__ void qkt_half(f32x16& p, const char* K_lds, int r32, int hi, int kh, const char* qf, bf16x8 q0) {
;     p = f32x16{};
;     const char* kb[4];
; #pragma unroll
;     for (int dd = 0; dd < 4; ++dd) kb[dd] = K_lds + KB * SHM_K + kh * 8192 + KSWZ(r32, (dd * 16 + hi * 8) * 2);
; #pragma unroll
;     for (int d0 = 0; d0 < 8; ++d0) { const bf16x8 b0 = *reinterpret_cast<const bf16x8*>(kb[d0 & 3] + (d0 >> 2) * 128); const bf16x8 q = d0 == 0 ? q0 : *reinterpret_cast<const bf16x8*>(qf + (d0 - 1) * 1024); p = __builtin_amdgcn_mfma_f32_32x32x16_bf16(b0, q, p, 0, 0, 0); }
.LBB0_369:
	ds_read_b128 v[184:187], v220 offset:16384
	ds_read_b128 v[180:183], v220 offset:17408
	ds_read_b128 v[64:67], v211
	ds_read_b128 v[68:71], v211 offset:128
	s_waitcnt lgkmcnt(1)
	v_mfma_f32_32x32x16_bf16 v[128:143], v[64:67], v[144:147], 0
	ds_read_b128 v[64:67], v212
	ds_read_b128 v[72:75], v210
	ds_read_b128 v[76:79], v210 offset:1024
	ds_read_b128 v[80:83], v212 offset:128
	s_waitcnt lgkmcnt(2)
	v_mfma_f32_32x32x16_bf16 v[128:143], v[64:67], v[72:75], v[128:143]
	ds_read_b128 v[64:67], v213
	ds_read_b128 v[72:75], v213 offset:128
	s_waitcnt lgkmcnt(1)
	v_mfma_f32_32x32x16_bf16 v[128:143], v[64:67], v[76:79], v[128:143]
	ds_read_b128 v[64:67], v214
	ds_read_b128 v[76:79], v210 offset:2048
	ds_read_b128 v[84:87], v210 offset:3072
	ds_read_b128 v[88:91], v214 offset:128
	s_waitcnt lgkmcnt(2)
	v_mfma_f32_32x32x16_bf16 v[128:143], v[64:67], v[76:79], v[128:143]
	s_waitcnt lgkmcnt(1)
	v_mfma_f32_32x32x16_bf16 v[128:143], v[68:71], v[84:87], v[128:143]
	ds_read_b128 v[64:67], v210 offset:4096
	ds_read_b128 v[68:71], v210 offset:5120
	s_waitcnt lgkmcnt(1)
	v_mfma_f32_32x32x16_bf16 v[128:143], v[80:83], v[64:67], v[128:143]
	ds_read_b128 v[64:67], v210 offset:6144
	s_waitcnt lgkmcnt(1)
	v_mfma_f32_32x32x16_bf16 v[128:143], v[72:75], v[68:71], v[128:143]
	s_waitcnt lgkmcnt(0)
	v_mfma_f32_32x32x16_bf16 v[128:143], v[88:91], v[64:67], v[128:143]
	s_mov_b64 s[4:5], -1
	s_and_b64 vcc, exec, s[48:49]
	s_cbranch_vccz .LBB0_371
	ds_read_b64_tr_b16 v[80:81], v194 offset:0xc000
	ds_read_b64_tr_b16 v[82:83], v194 offset:0xc800
	ds_read_b64_tr_b16 v[84:85], v194 offset:0xd000
	ds_read_b64_tr_b16 v[86:87], v194 offset:0xd800
	ds_read_b64_tr_b16 v[88:89], v194 offset:0xe000
	ds_read_b64_tr_b16 v[90:91], v194 offset:0xe800
	ds_read_b64_tr_b16 v[92:93], v194 offset:0xf000
	ds_read_b64_tr_b16 v[94:95], v194 offset:0xf800
	s_waitcnt lgkmcnt(0)
	s_nop 0
	v_mfma_f32_32x32x16_bf16 v[64:79], v[184:187], v[80:83], v[0:15]
	ds_read_b64_tr_b16 v[96:97], v194 offset:0xc200
	ds_read_b64_tr_b16 v[98:99], v194 offset:0xca00
	ds_read_b64_tr_b16 v[100:101], v194 offset:0xd200
	ds_read_b64_tr_b16 v[102:103], v194 offset:0xda00
	ds_read_b64_tr_b16 v[104:105], v194 offset:0xe200
	ds_read_b64_tr_b16 v[106:107], v194 offset:0xea00
	ds_read_b64_tr_b16 v[108:109], v194 offset:0xf200
	v_mfma_f32_32x32x16_bf16 v[64:79], v[180:183], v[84:87], v[64:79]
	ds_read_b64_tr_b16 v[110:111], v194 offset:0xfa00
	v_mfma_f32_32x32x16_bf16 v[64:79], v[172:175], v[88:91], v[64:79]
	v_mfma_f32_32x32x16_bf16 v[64:79], v[176:179], v[92:95], v[64:79]
	s_waitcnt lgkmcnt(0)
	v_mfma_f32_32x32x16_bf16 v[80:95], v[184:187], v[96:99], v[16:31]
	ds_read_b64_tr_b16 v[112:113], v194 offset:0xc400
	ds_read_b64_tr_b16 v[114:115], v194 offset:0xcc00
	ds_read_b64_tr_b16 v[116:117], v194 offset:0xd400
	ds_read_b64_tr_b16 v[118:119], v194 offset:0xdc00
	ds_read_b64_tr_b16 v[120:121], v194 offset:0xe400
	ds_read_b64_tr_b16 v[122:123], v194 offset:0xec00
	ds_read_b64_tr_b16 v[124:125], v194 offset:0xf400
	v_mfma_f32_32x32x16_bf16 v[80:95], v[180:183], v[100:103], v[80:95]
	ds_read_b64_tr_b16 v[126:127], v194 offset:0xfc00
	s_add_i32 s38, s87, -3
	s_add_i32 s50, s53, 1
	s_and_b64 s[4:5], s[46:47], exec
	s_cselect_b32 s4, s38, s50
	s_lshl_b32 s4, s4, 6
	s_cmp_le_i32 s4, s86
	s_cbranch_scc0 .Lm0_h1B_mk

; template <int VB, bool SK>
; __device__ __forceinline__ void pv_tile(f32x16* o, int vb0, bf16x8 pa0, bf16x8 pa1, bf16x8 pa2, bf16x8 pa3, bool act) {
;     if (SK && !act) return;
.LBB0_371:
	s_andn2_b64 vcc, exec, s[4:5]
	s_cbranch_vccnz .LBB0_373
	ds_read_b64_tr_b16 v[80:81], v194 offset:0x8000
	ds_read_b64_tr_b16 v[82:83], v194 offset:0x8800
	ds_read_b64_tr_b16 v[84:85], v194 offset:0x9000
	ds_read_b64_tr_b16 v[86:87], v194 offset:0x9800
	ds_read_b64_tr_b16 v[88:89], v194 offset:0xa000
	ds_read_b64_tr_b16 v[90:91], v194 offset:0xa800
	ds_read_b64_tr_b16 v[92:93], v194 offset:0xb000
	ds_read_b64_tr_b16 v[94:95], v194 offset:0xb800
	s_waitcnt lgkmcnt(0)
	s_nop 0
	v_mfma_f32_32x32x16_bf16 v[64:79], v[172:175], v[80:83], v[0:15]
	ds_read_b64_tr_b16 v[96:97], v194 offset:0x8200
	ds_read_b64_tr_b16 v[98:99], v194 offset:0x8a00
	ds_read_b64_tr_b16 v[100:101], v194 offset:0x9200
	ds_read_b64_tr_b16 v[102:103], v194 offset:0x9a00
	ds_read_b64_tr_b16 v[104:105], v194 offset:0xa200
	ds_read_b64_tr_b16 v[106:107], v194 offset:0xaa00
	ds_read_b64_tr_b16 v[108:109], v194 offset:0xb200
	v_mfma_f32_32x32x16_bf16 v[64:79], v[176:179], v[84:87], v[64:79]
	ds_read_b64_tr_b16 v[110:111], v194 offset:0xba00
	v_mfma_f32_32x32x16_bf16 v[64:79], v[184:187], v[88:91], v[64:79]
	v_mfma_f32_32x32x16_bf16 v[64:79], v[180:183], v[92:95], v[64:79]
	s_waitcnt lgkmcnt(0)
	v_mfma_f32_32x32x16_bf16 v[80:95], v[172:175], v[96:99], v[16:31]
	ds_read_b64_tr_b16 v[112:113], v194 offset:0x8400
	ds_read_b64_tr_b16 v[114:115], v194 offset:0x8c00
	ds_read_b64_tr_b16 v[116:117], v194 offset:0x9400
	ds_read_b64_tr_b16 v[118:119], v194 offset:0x9c00
	ds_read_b64_tr_b16 v[120:121], v194 offset:0xa400
	ds_read_b64_tr_b16 v[122:123], v194 offset:0xac00
	ds_read_b64_tr_b16 v[124:125], v194 offset:0xb400
	v_mfma_f32_32x32x16_bf16 v[80:95], v[176:179], v[100:103], v[80:95]
	ds_read_b64_tr_b16 v[126:127], v194 offset:0xbc00
	s_add_i32 s38, s87, -3
	s_add_i32 s50, s53, 1
	s_and_b64 s[4:5], s[46:47], exec
	s_cselect_b32 s4, s38, s50
	s_lshl_b32 s4, s4, 6
	s_cmp_le_i32 s4, s86
	s_cbranch_scc0 .Lm0_h1A_mk

.LBB0_373:
	v_cmp_gt_f32_e32 vcc, 1.0, v229
	s_cbranch_vccnz .Lm0_r1

; template <int KB> __device__ __forceinline__ void qkt_half(f32x16& p, const char* K_lds, int r32, int hi, int kh, const char* qf, bf16x8 q0) {
;     p = f32x16{};
;     const char* kb[4];
; #pragma unroll
;     for (int dd = 0; dd < 4; ++dd) kb[dd] = K_lds + KB * SHM_K + kh * 8192 + KSWZ(r32, (dd * 16 + hi * 8) * 2);
; #pragma unroll
;     for (int d0 = 0; d0 < 8; ++d0) { const bf16x8 b0 = *reinterpret_cast<const bf16x8*>(kb[d0 & 3] + (d0 >> 2) * 128); const bf16x8 q = d0 == 0 ? q0 : *reinterpret_cast<const bf16x8*>(qf + (d0 - 1) * 1024); p = __builtin_amdgcn_mfma_f32_32x32x16_bf16(b0, q, p, 0, 0, 0); }
.LBB0_386:
	ds_read_b128 v[184:187], v220
	ds_read_b128 v[180:183], v220 offset:1024
	ds_read_b128 v[0:3], v222
	ds_read_b128 v[4:7], v222 offset:128
	s_waitcnt lgkmcnt(1)
	v_mfma_f32_32x32x16_bf16 v[128:143], v[0:3], v[144:147], 0
	ds_read_b128 v[0:3], v223
	ds_read_b128 v[8:11], v210
	ds_read_b128 v[12:15], v210 offset:1024
	ds_read_b128 v[16:19], v223 offset:128
	s_waitcnt lgkmcnt(2)
	v_mfma_f32_32x32x16_bf16 v[128:143], v[0:3], v[8:11], v[128:143]
	ds_read_b128 v[0:3], v224
	ds_read_b128 v[8:11], v224 offset:128
	s_waitcnt lgkmcnt(1)
	v_mfma_f32_32x32x16_bf16 v[128:143], v[0:3], v[12:15], v[128:143]
	ds_read_b128 v[0:3], v225
	ds_read_b128 v[12:15], v210 offset:2048
	ds_read_b128 v[20:23], v210 offset:3072
	ds_read_b128 v[24:27], v225 offset:128
	s_waitcnt lgkmcnt(2)
	v_mfma_f32_32x32x16_bf16 v[128:143], v[0:3], v[12:15], v[128:143]
	s_waitcnt lgkmcnt(1)
	v_mfma_f32_32x32x16_bf16 v[128:143], v[4:7], v[20:23], v[128:143]
	ds_read_b128 v[0:3], v210 offset:4096
	ds_read_b128 v[4:7], v210 offset:5120
	s_waitcnt lgkmcnt(1)
	v_mfma_f32_32x32x16_bf16 v[128:143], v[16:19], v[0:3], v[128:143]
	ds_read_b128 v[0:3], v210 offset:6144
	s_waitcnt lgkmcnt(1)
	v_mfma_f32_32x32x16_bf16 v[128:143], v[8:11], v[4:7], v[128:143]
	s_waitcnt lgkmcnt(0)
	v_mfma_f32_32x32x16_bf16 v[128:143], v[24:27], v[0:3], v[128:143]
	s_mov_b64 s[4:5], -1
	s_and_b64 vcc, exec, s[48:49]
	s_cbranch_vccz .LBB0_388
	ds_read_b64_tr_b16 v[16:17], v194 offset:0x4000
	ds_read_b64_tr_b16 v[18:19], v194 offset:0x4800
	ds_read_b64_tr_b16 v[20:21], v194 offset:0x5000
	ds_read_b64_tr_b16 v[22:23], v194 offset:0x5800
	ds_read_b64_tr_b16 v[24:25], v194 offset:0x6000
	ds_read_b64_tr_b16 v[26:27], v194 offset:0x6800
	ds_read_b64_tr_b16 v[28:29], v194 offset:0x7000
	ds_read_b64_tr_b16 v[30:31], v194 offset:0x7800
	s_waitcnt lgkmcnt(0)
	s_nop 0
	v_mfma_f32_32x32x16_bf16 v[0:15], v[184:187], v[16:19], v[64:79]
	ds_read_b64_tr_b16 v[32:33], v194 offset:0x4200
	ds_read_b64_tr_b16 v[34:35], v194 offset:0x4a00
	ds_read_b64_tr_b16 v[36:37], v194 offset:0x5200
	ds_read_b64_tr_b16 v[38:39], v194 offset:0x5a00
	ds_read_b64_tr_b16 v[40:41], v194 offset:0x6200
	ds_read_b64_tr_b16 v[42:43], v194 offset:0x6a00
	ds_read_b64_tr_b16 v[44:45], v194 offset:0x7200
	v_mfma_f32_32x32x16_bf16 v[0:15], v[180:183], v[20:23], v[0:15]
	ds_read_b64_tr_b16 v[46:47], v194 offset:0x7a00
	v_mfma_f32_32x32x16_bf16 v[0:15], v[172:175], v[24:27], v[0:15]
	v_mfma_f32_32x32x16_bf16 v[0:15], v[176:179], v[28:31], v[0:15]
	s_waitcnt lgkmcnt(0)
	v_mfma_f32_32x32x16_bf16 v[16:31], v[184:187], v[32:35], v[80:95]
	ds_read_b64_tr_b16 v[48:49], v194 offset:0x4400
	ds_read_b64_tr_b16 v[50:51], v194 offset:0x4c00
	ds_read_b64_tr_b16 v[52:53], v194 offset:0x5400
	ds_read_b64_tr_b16 v[54:55], v194 offset:0x5c00
	ds_read_b64_tr_b16 v[56:57], v194 offset:0x6400
	ds_read_b64_tr_b16 v[58:59], v194 offset:0x6c00
	ds_read_b64_tr_b16 v[60:61], v194 offset:0x7400
	v_mfma_f32_32x32x16_bf16 v[16:31], v[180:183], v[36:39], v[16:31]
	ds_read_b64_tr_b16 v[62:63], v194 offset:0x7c00
	s_and_b64 s[4:5], s[46:47], exec
	s_cselect_b32 s4, s89, s53
	s_lshl_b32 s4, s4, 6
	s_cmp_le_i32 s4, s86
	s_cbranch_scc0 .Lm0_h2B_mk

; template <int VB, bool SK>
; __device__ __forceinline__ void pv_tile(f32x16* o, int vb0, bf16x8 pa0, bf16x8 pa1, bf16x8 pa2, bf16x8 pa3, bool act) {
;     if (SK && !act) return;
.LBB0_388:
	s_andn2_b64 vcc, exec, s[4:5]
	s_cbranch_vccnz .LBB0_390
	ds_read_b64_tr_b16 v[16:17], v194 offset:0
	ds_read_b64_tr_b16 v[18:19], v194 offset:0x800
	ds_read_b64_tr_b16 v[20:21], v194 offset:0x1000
	ds_read_b64_tr_b16 v[22:23], v194 offset:0x1800
	ds_read_b64_tr_b16 v[24:25], v194 offset:0x2000
	ds_read_b64_tr_b16 v[26:27], v194 offset:0x2800
	ds_read_b64_tr_b16 v[28:29], v194 offset:0x3000
	ds_read_b64_tr_b16 v[30:31], v194 offset:0x3800
	s_waitcnt lgkmcnt(0)
	s_nop 0
	v_mfma_f32_32x32x16_bf16 v[0:15], v[172:175], v[16:19], v[64:79]
	ds_read_b64_tr_b16 v[32:33], v194 offset:0x200
	ds_read_b64_tr_b16 v[34:35], v194 offset:0xa00
	ds_read_b64_tr_b16 v[36:37], v194 offset:0x1200
	ds_read_b64_tr_b16 v[38:39], v194 offset:0x1a00
	ds_read_b64_tr_b16 v[40:41], v194 offset:0x2200
	ds_read_b64_tr_b16 v[42:43], v194 offset:0x2a00
	ds_read_b64_tr_b16 v[44:45], v194 offset:0x3200
	v_mfma_f32_32x32x16_bf16 v[0:15], v[176:179], v[20:23], v[0:15]
	ds_read_b64_tr_b16 v[46:47], v194 offset:0x3a00
	v_mfma_f32_32x32x16_bf16 v[0:15], v[184:187], v[24:27], v[0:15]
	v_mfma_f32_32x32x16_bf16 v[0:15], v[180:183], v[28:31], v[0:15]
	s_waitcnt lgkmcnt(0)
	v_mfma_f32_32x32x16_bf16 v[16:31], v[172:175], v[32:35], v[80:95]
	ds_read_b64_tr_b16 v[48:49], v194 offset:0x400
	ds_read_b64_tr_b16 v[50:51], v194 offset:0xc00
	ds_read_b64_tr_b16 v[52:53], v194 offset:0x1400
	ds_read_b64_tr_b16 v[54:55], v194 offset:0x1c00
	ds_read_b64_tr_b16 v[56:57], v194 offset:0x2400
	ds_read_b64_tr_b16 v[58:59], v194 offset:0x2c00
	ds_read_b64_tr_b16 v[60:61], v194 offset:0x3400
	v_mfma_f32_32x32x16_bf16 v[16:31], v[176:179], v[36:39], v[16:31]
	ds_read_b64_tr_b16 v[62:63], v194 offset:0x3c00
	s_and_b64 s[4:5], s[46:47], exec
	s_cselect_b32 s4, s89, s53
	s_lshl_b32 s4, s4, 6
	s_cmp_le_i32 s4, s86
	s_cbranch_scc0 .Lm0_h2A_mk

.LBB0_390:
	v_cmp_gt_f32_e32 vcc, 1.0, v230
	s_cbranch_vccnz .Lm0_r2

.Lm0_r1:
	s_and_saveexec_b64 s[4:5], s[2:3]
	ds_write_b32 v221, v229
	s_or_b64 exec, exec, s[4:5]
	s_waitcnt lgkmcnt(0)
	v_add_u32_e32 v12, s52, v196
	ds_read_b128 v[0:3], v12 offset:96
	ds_read_b128 v[4:7], v12 offset:64
	ds_read_b128 v[8:11], v12 offset:32
	ds_read_b128 v[12:15], v12
	s_waitcnt lgkmcnt(3)
	v_pk_mul_f32 v[76:77], v[76:77], v[0:1]
	s_waitcnt lgkmcnt(2)
	v_pk_mul_f32 v[72:73], v[72:73], v[4:5]
	s_waitcnt lgkmcnt(1)
	v_pk_mul_f32 v[68:69], v[68:69], v[8:9]
	v_pk_mul_f32 v[78:79], v[78:79], v[2:3]
	v_pk_mul_f32 v[74:75], v[74:75], v[6:7]
	v_pk_mul_f32 v[70:71], v[70:71], v[10:11]
	s_waitcnt lgkmcnt(0)
	v_pk_mul_f32 v[66:67], v[66:67], v[14:15]
	v_pk_mul_f32 v[64:65], v[64:65], v[12:13]
	v_pk_mul_f32 v[92:93], v[92:93], v[0:1]
	v_pk_mul_f32 v[88:89], v[88:89], v[4:5]
	v_pk_mul_f32 v[84:85], v[84:85], v[8:9]
	v_pk_mul_f32 v[94:95], v[94:95], v[2:3]
	v_pk_mul_f32 v[90:91], v[90:91], v[6:7]
	v_pk_mul_f32 v[86:87], v[86:87], v[10:11]
	v_pk_mul_f32 v[82:83], v[82:83], v[14:15]
	v_pk_mul_f32 v[80:81], v[80:81], v[12:13]
	v_pk_mul_f32 v[108:109], v[108:109], v[0:1]
	v_pk_mul_f32 v[104:105], v[104:105], v[4:5]
	v_pk_mul_f32 v[100:101], v[100:101], v[8:9]
	v_pk_mul_f32 v[110:111], v[110:111], v[2:3]
	v_pk_mul_f32 v[106:107], v[106:107], v[6:7]
	v_pk_mul_f32 v[102:103], v[102:103], v[10:11]
	v_pk_mul_f32 v[98:99], v[98:99], v[14:15]
	v_pk_mul_f32 v[96:97], v[96:97], v[12:13]
	v_pk_mul_f32 v[124:125], v[124:125], v[0:1]
	v_pk_mul_f32 v[120:121], v[120:121], v[4:5]
	v_pk_mul_f32 v[116:117], v[116:117], v[8:9]
	v_pk_mul_f32 v[126:127], v[126:127], v[2:3]
	v_pk_mul_f32 v[122:123], v[122:123], v[6:7]
	v_pk_mul_f32 v[118:119], v[118:119], v[10:11]
	v_pk_mul_f32 v[114:115], v[114:115], v[14:15]
	v_pk_mul_f32 v[112:113], v[112:113], v[12:13]
	s_branch .LBB0_377
.Lm0_r2:
	s_and_saveexec_b64 s[4:5], s[2:3]
	ds_write_b32 v221, v230
	s_or_b64 exec, exec, s[4:5]
	s_waitcnt lgkmcnt(0)
	v_add_u32_e32 v76, s52, v196
	ds_read_b128 v[64:67], v76 offset:96
	ds_read_b128 v[68:71], v76 offset:64
	ds_read_b128 v[72:75], v76 offset:32
	ds_read_b128 v[76:79], v76
	s_waitcnt lgkmcnt(3)
	v_pk_mul_f32 v[12:13], v[12:13], v[64:65]
	s_waitcnt lgkmcnt(2)
	v_pk_mul_f32 v[8:9], v[8:9], v[68:69]
	s_waitcnt lgkmcnt(1)
	v_pk_mul_f32 v[4:5], v[4:5], v[72:73]
	v_pk_mul_f32 v[14:15], v[14:15], v[66:67]
	v_pk_mul_f32 v[10:11], v[10:11], v[70:71]
	v_pk_mul_f32 v[6:7], v[6:7], v[74:75]
	s_waitcnt lgkmcnt(0)
	v_pk_mul_f32 v[2:3], v[2:3], v[78:79]
	v_pk_mul_f32 v[0:1], v[0:1], v[76:77]
	v_pk_mul_f32 v[28:29], v[28:29], v[64:65]
	v_pk_mul_f32 v[24:25], v[24:25], v[68:69]
	v_pk_mul_f32 v[20:21], v[20:21], v[72:73]
	v_pk_mul_f32 v[30:31], v[30:31], v[66:67]
	v_pk_mul_f32 v[26:27], v[26:27], v[70:71]
	v_pk_mul_f32 v[22:23], v[22:23], v[74:75]
	v_pk_mul_f32 v[18:19], v[18:19], v[78:79]
	v_pk_mul_f32 v[16:17], v[16:17], v[76:77]
	v_pk_mul_f32 v[44:45], v[44:45], v[64:65]
	v_pk_mul_f32 v[40:41], v[40:41], v[68:69]
	v_pk_mul_f32 v[36:37], v[36:37], v[72:73]
	v_pk_mul_f32 v[46:47], v[46:47], v[66:67]
	v_pk_mul_f32 v[42:43], v[42:43], v[70:71]
	v_pk_mul_f32 v[38:39], v[38:39], v[74:75]
	v_pk_mul_f32 v[34:35], v[34:35], v[78:79]
	v_pk_mul_f32 v[32:33], v[32:33], v[76:77]
	v_pk_mul_f32 v[60:61], v[60:61], v[64:65]
	v_pk_mul_f32 v[56:57], v[56:57], v[68:69]
	v_pk_mul_f32 v[52:53], v[52:53], v[72:73]
	v_pk_mul_f32 v[62:63], v[62:63], v[66:67]
	v_pk_mul_f32 v[58:59], v[58:59], v[70:71]
	v_pk_mul_f32 v[54:55], v[54:55], v[74:75]
	v_pk_mul_f32 v[50:51], v[50:51], v[78:79]
	v_pk_mul_f32 v[48:49], v[48:49], v[76:77]
	s_branch .LBB0_394
.Lm0_h1B_mk:
	v_mov_b32_e32 v128, v204
	v_mov_b32_e32 v129, v204
	v_mov_b32_e32 v130, v204
	v_mov_b32_e32 v131, v204
	v_mov_b32_e32 v132, v204
	v_mov_b32_e32 v133, v204
	v_mov_b32_e32 v134, v204
	v_mov_b32_e32 v135, v204
	v_mov_b32_e32 v136, v204
	v_mov_b32_e32 v137, v204
	v_mov_b32_e32 v138, v204
	v_mov_b32_e32 v139, v204
	v_mov_b32_e32 v140, v204
	v_mov_b32_e32 v141, v204
	v_mov_b32_e32 v142, v204
	v_mov_b32_e32 v143, v204
	s_branch .Lm0_h1B_nm
